# attention context staging: the four V chunk loads issued together with counted waits
# baseline (speedup 1.0000x reference)
; #define LAS __attribute__((address_space(3)))
; __device__ __forceinline__ unsigned pk2(float lo, float hi) { unsigned r; asm("v_cvt_pk_bf16_f32 %0, %1, %2" : "=v"(r) : "v"(lo), "v"(hi)); return r; }
; __device__ __forceinline__ float bflo(unsigned u) { return __uint_as_float(u << 16); }
; __device__ __forceinline__ float bfhi(unsigned u) { return __uint_as_float(u & 0xFFFF0000u); }
; __device__ __forceinline__ void attn_stage(LAS unsigned char* Kl, LAS unsigned char* Vl, const bf16_t* qk, const bf16_t* Vt, int tok0, int g, int tid, const float* kgain, const float2* rope, bool do_rope) {
;     const int row = tid >> 3, piece = tid & 7;
;     const u32x4 kraw = *(const u32x4*)(qk + (size_t)(tok0 + row) * 1280 + 1024 + 64 * g + 8 * piece);
;     float y[8] = {bflo(kraw.x), bfhi(kraw.x), bflo(kraw.y), bfhi(kraw.y), bflo(kraw.z), bfhi(kraw.z), bflo(kraw.w), bfhi(kraw.w)};
;     float ss = 0.f;
; #pragma unroll
;     for (int i = 0; i < 8; ++i) ss += y[i] * y[i];
;     ss += __shfl_xor(ss, 1); ss += __shfl_xor(ss, 2); ss += __shfl_xor(ss, 4);
;     const float rs = rsqrtf(ss * (1.f / 64.f) + 1e-6f);
;     const f32x4 g0 = *(const f32x4*)(kgain + 8 * piece), g1 = *(const f32x4*)(kgain + 8 * piece + 4);
; #pragma unroll
;     for (int i = 0; i < 4; ++i) { y[i] *= rs * g0[i]; y[4 + i] *= rs * g1[i]; }
;     float py[8];
; #pragma unroll
;     for (int i = 0; i < 8; ++i) py[i] = __shfl_xor(y[i], 2);
;     if (do_rope) {
;         const int token = tok0 + row, pos = (piece < 4) ? (token >> 6) : (token & 63);
;         const float2* cs = rope + pos * 16 + 8 * (piece & 1);
; #pragma unroll
;         for (int i = 0; i < 8; ++i) { const float2 t = cs[i]; y[i] = (piece & 2) ? (py[i] * t.y + y[i] * t.x) : (y[i] * t.x - py[i] * t.y); }
;     }
;     u32x4 kv; kv.x = pk2(y[0], y[1]); kv.y = pk2(y[2], y[3]); kv.z = pk2(y[4], y[5]); kv.w = pk2(y[6], y[7]);
;     *(LAS u32x4*)(Kl + row * 144 + piece * 16) = kv;
;     const u32x4 vv = *(const u32x4*)(Vt + (size_t)(g * 64 + row) * MTOT + tok0 + 8 * piece);
;     LAS u32x2* vd = (LAS u32x2*)(Vl + row * 136 + piece * 16); vd[0] = (u32x2){vv.x, vv.y}; vd[1] = (u32x2){vv.z, vv.w};
; __device__ __forceinline__ void attn_phase(const Params& P, LAS unsigned char* lds) {
;     ...
;         for (int ci = 0; ci < 4; ++ci) attn_stage(lds + ci * KSZ, lds + VBASE + ci * VSZ, qk, Vt, SEQ + 64 * ci, g, tid, P.k_gain, rope, false);
.LBB0_723:
	v_readlane_b32 s8, v252, 30
	v_readlane_b32 s9, v252, 31
	s_lshl_b32 s8, s35, 1
	s_nop 0
	v_lshl_add_u64 v[34:35], v[94:95], 0, s[8:9]
	global_load_dwordx4 v[230:233], v[34:35], off offset:2048
	v_lshl_add_u64 v[246:247], v[96:97], 0, s[8:9]
	global_load_dwordx4 v[234:237], v[246:247], off offset:2048
	v_lshl_add_u64 v[246:247], v[98:99], 0, s[8:9]
	global_load_dwordx4 v[238:241], v[246:247], off offset:2048
	v_lshl_add_u64 v[246:247], v[100:101], 0, s[8:9]
	global_load_dwordx4 v[242:245], v[246:247], off offset:2048
	s_barrier
	s_nop 0
	s_mov_b32 s2, 0x800000
	s_mov_b32 s0, 0x8000
	v_mov_b32_e32 v175, v1
	s_mov_b32 s1, s9
	v_ashrrev_i32_e32 v109, 31, v108
	s_movk_i32 s48, 0x7000
	s_waitcnt vmcnt(0)
	v_mov_b64_e32 v[34:35], v[230:231]
	v_mov_b64_e32 v[36:37], v[232:233]
	v_lshlrev_b32_e32 v42, 16, v34
	v_and_b32_e32 v43, 0xffff0000, v34
	v_pk_mul_f32 v[38:39], v[42:43], v[42:43]
	v_and_b32_e32 v44, 0xffff0000, v35
	v_lshlrev_b32_e32 v45, 16, v35
	v_pk_mul_f32 v[34:35], v[44:45], v[44:45]
	v_add_f32_e32 v38, v38, v39
	v_and_b32_e32 v46, 0xffff0000, v36
	v_lshlrev_b32_e32 v47, 16, v36
	v_add_f32_e32 v35, v35, v38
	v_pk_mul_f32 v[40:41], v[46:47], v[46:47]
	v_add_f32_e32 v34, v34, v35
	v_and_b32_e32 v48, 0xffff0000, v37
	v_lshlrev_b32_e32 v49, 16, v37
	v_add_f32_e32 v34, v41, v34
	v_pk_mul_f32 v[36:37], v[48:49], v[48:49]
	v_add_f32_e32 v34, v40, v34
	v_add_f32_e32 v34, v37, v34
	v_add_f32_e32 v34, v36, v34
	ds_bpermute_b32 v35, v180, v34
	s_waitcnt lgkmcnt(0)
	v_add_f32_e32 v34, v34, v35
	ds_bpermute_b32 v35, v181, v34
	s_waitcnt lgkmcnt(0)
	v_add_f32_e32 v34, v34, v35
	ds_bpermute_b32 v35, v182, v34
	s_waitcnt lgkmcnt(0)
	v_add_f32_e32 v34, v34, v35
	v_fmamk_f32 v34, v34, 0x3c800000, v197
	v_cmp_gt_f32_e32 vcc, s2, v34
	v_mul_f32_e32 v35, 0x4b800000, v34
	s_nop 0
	v_cndmask_b32_e32 v34, v34, v35, vcc
	v_rsq_f32_e32 v34, v34
	s_nop 0
	v_mul_f32_e32 v35, 0x45800000, v34
	v_cndmask_b32_e32 v50, v34, v35, vcc
	v_mov_b64_e32 v[34:35], v[222:223]
	v_mov_b64_e32 v[36:37], v[224:225]
	v_mov_b64_e32 v[38:39], v[226:227]
	v_mov_b64_e32 v[40:41], v[228:229]
	v_mul_f32_e32 v51, v38, v50
	v_mul_f32_e32 v42, v51, v42
	v_mul_f32_e32 v51, v34, v50
	v_mul_f32_e32 v47, v51, v47
	v_mul_f32_e32 v51, v39, v50
	v_mul_f32_e32 v43, v51, v43
	v_mul_f32_e32 v51, v35, v50
	v_mul_f32_e32 v46, v51, v46
	v_mul_f32_e32 v51, v40, v50
	v_mul_f32_e32 v45, v51, v45
	v_mul_f32_e32 v51, v36, v50
	v_mul_f32_e32 v49, v51, v49
	v_mul_f32_e32 v51, v41, v50
	v_mul_f32_e32 v44, v51, v44
	v_mul_f32_e32 v50, v37, v50
	v_cvt_pk_bf16_f32 v42, v42, v43
	v_mul_f32_e32 v48, v50, v48
	v_cvt_pk_bf16_f32 v43, v45, v44
	v_cvt_pk_bf16_f32 v44, v47, v46
	v_cvt_pk_bf16_f32 v45, v49, v48
	ds_write_b128 v107, v[42:45]
	v_add_co_u32_e32 v42, vcc, s0, v112
	v_writelane_b32 v252, s0, 30
	s_nop 0
	v_addc_co_u32_e32 v43, vcc, 0, v113, vcc
	global_load_dwordx4 v[44:47], v[42:43], off
	global_load_dwordx4 v[222:225], v[42:43], off offset:128
	global_load_dwordx4 v[226:229], v[42:43], off offset:256
	global_load_dwordx2 v[246:247], v[42:43], off offset:384
	global_load_dwordx2 v[198:199], v[42:43], off offset:392
	v_writelane_b32 v252, s1, 31
	s_waitcnt vmcnt(4)
	ds_write2_b64 v186, v[44:45], v[46:47] offset1:1
	v_mov_b64_e32 v[44:45], v[234:235]
	v_mov_b64_e32 v[46:47], v[236:237]
	v_lshlrev_b32_e32 v48, 16, v44
	v_and_b32_e32 v49, 0xffff0000, v44
	v_pk_mul_f32 v[50:51], v[48:49], v[48:49]
	v_and_b32_e32 v44, 0xffff0000, v45
	v_lshlrev_b32_e32 v45, 16, v45
	v_pk_mul_f32 v[52:53], v[44:45], v[44:45]
	v_add_f32_e32 v50, v50, v51
	v_and_b32_e32 v54, 0xffff0000, v46
	v_lshlrev_b32_e32 v55, 16, v46
	v_add_f32_e32 v50, v53, v50
	v_pk_mul_f32 v[56:57], v[54:55], v[54:55]
	v_add_f32_e32 v50, v52, v50
	v_and_b32_e32 v46, 0xffff0000, v47
	v_lshlrev_b32_e32 v47, 16, v47
	v_add_f32_e32 v50, v57, v50
	v_pk_mul_f32 v[58:59], v[46:47], v[46:47]
	v_add_f32_e32 v50, v56, v50
	v_add_f32_e32 v50, v59, v50
	v_add_f32_e32 v50, v58, v50
	ds_bpermute_b32 v51, v180, v50
	s_waitcnt lgkmcnt(0)
	v_add_f32_e32 v50, v50, v51
	ds_bpermute_b32 v51, v181, v50
	s_waitcnt lgkmcnt(0)
	v_add_f32_e32 v50, v50, v51
	ds_bpermute_b32 v51, v182, v50
	s_waitcnt lgkmcnt(0)
	v_add_f32_e32 v50, v50, v51
	v_fmamk_f32 v50, v50, 0x3c800000, v197
	v_cmp_gt_f32_e32 vcc, s2, v50
	v_mul_f32_e32 v51, 0x4b800000, v50
	s_nop 0
	v_cndmask_b32_e32 v50, v50, v51, vcc
	v_rsq_f32_e32 v50, v50
	s_nop 0
	v_mul_f32_e32 v51, 0x45800000, v50
	v_cndmask_b32_e32 v50, v50, v51, vcc
	v_mul_f32_e32 v53, v40, v50
	v_mul_f32_e32 v45, v53, v45
	v_mul_f32_e32 v53, v36, v50
	v_mul_f32_e32 v51, v38, v50
	v_mul_f32_e32 v52, v39, v50
	v_mul_f32_e32 v47, v53, v47
	v_mul_f32_e32 v53, v41, v50
	v_mul_f32_e32 v48, v51, v48
	v_mul_f32_e32 v51, v34, v50
	v_mul_f32_e32 v49, v52, v49
	v_mul_f32_e32 v52, v35, v50
	v_mul_f32_e32 v53, v53, v44
	v_mul_f32_e32 v44, v37, v50
	v_mul_f32_e32 v51, v51, v55
	v_mul_f32_e32 v52, v52, v54
	v_mul_f32_e32 v50, v44, v46
	v_cvt_pk_bf16_f32 v44, v48, v49
	v_cvt_pk_bf16_f32 v45, v45, v53
	v_cvt_pk_bf16_f32 v46, v51, v52
	v_cvt_pk_bf16_f32 v47, v47, v50
	ds_write_b128 v107, v[44:47] offset:9216
	s_nop 0
	s_waitcnt vmcnt(3)
	ds_write2_b64 v114, v[222:223], v[224:225] offset1:1
	v_mov_b64_e32 v[44:45], v[238:239]
	v_mov_b64_e32 v[46:47], v[240:241]
	v_lshlrev_b32_e32 v48, 16, v44
	v_and_b32_e32 v49, 0xffff0000, v44
	v_pk_mul_f32 v[50:51], v[48:49], v[48:49]
	v_and_b32_e32 v44, 0xffff0000, v45
	v_lshlrev_b32_e32 v45, 16, v45
	v_pk_mul_f32 v[52:53], v[44:45], v[44:45]
	v_add_f32_e32 v50, v50, v51
	v_and_b32_e32 v54, 0xffff0000, v46
	v_lshlrev_b32_e32 v55, 16, v46
	v_add_f32_e32 v50, v53, v50
	v_pk_mul_f32 v[56:57], v[54:55], v[54:55]
	v_add_f32_e32 v50, v52, v50
	v_and_b32_e32 v46, 0xffff0000, v47
	v_lshlrev_b32_e32 v47, 16, v47
	v_add_f32_e32 v50, v57, v50
	v_pk_mul_f32 v[58:59], v[46:47], v[46:47]
	v_add_f32_e32 v50, v56, v50
	v_add_f32_e32 v50, v59, v50
	v_add_f32_e32 v50, v58, v50
	ds_bpermute_b32 v51, v180, v50
	s_waitcnt lgkmcnt(0)
; #define LAS __attribute__((address_space(3)))
; __device__ __forceinline__ unsigned pk2(float lo, float hi) { unsigned r; asm("v_cvt_pk_bf16_f32 %0, %1, %2" : "=v"(r) : "v"(lo), "v"(hi)); return r; }
; __device__ __forceinline__ void attn_chunk(LAS unsigned char* Kl, LAS unsigned char* Vl, const bf16x8 (&qf)[4], f32x16 (&o)[2], float& m, float& l, int q, int half, int ii, int maskmode) {
;     ...
;     for (int kb = 0; kb < 2; ++kb) {
; #pragma unroll
;         for (int r = 0; r < 16; ++r) s[kb][r] = 0.f;
; #pragma unroll
;         for (int ks = 0; ks < 4; ++ks) { const bf16x8 kf = *(const LAS bf16x8*)(Kl + (32 * kb + q) * 144 + (2 * ks + half) * 16); s[kb] = __builtin_amdgcn_mfma_f32_32x32x16_bf16(kf, qf[ks], s[kb], 0, 0, 0); }
; __device__ __forceinline__ void attn_stage(LAS unsigned char* Kl, LAS unsigned char* Vl, const bf16_t* qk, const bf16_t* Vt, int tok0, int g, int tid, const float* kgain, const float2* rope, bool do_rope) {
;     ...
;     const f32x4 g0 = *(const f32x4*)(kgain + 8 * piece), g1 = *(const f32x4*)(kgain + 8 * piece + 4);
; #pragma unroll
;     for (int i = 0; i < 4; ++i) { y[i] *= rs * g0[i]; y[4 + i] *= rs * g1[i]; }
;     float py[8];
; #pragma unroll
;     for (int i = 0; i < 8; ++i) py[i] = __shfl_xor(y[i], 2);
;     if (do_rope) {
;         const int token = tok0 + row, pos = (piece < 4) ? (token >> 6) : (token & 63);
;         const float2* cs = rope + pos * 16 + 8 * (piece & 1);
; #pragma unroll
;         for (int i = 0; i < 8; ++i) { const float2 t = cs[i]; y[i] = (piece & 2) ? (py[i] * t.y + y[i] * t.x) : (y[i] * t.x - py[i] * t.y); }
;     }
;     u32x4 kv; kv.x = pk2(y[0], y[1]); kv.y = pk2(y[2], y[3]); kv.z = pk2(y[4], y[5]); kv.w = pk2(y[6], y[7]);
;     *(LAS u32x4*)(Kl + row * 144 + piece * 16) = kv;
;     const u32x4 vv = *(const u32x4*)(Vt + (size_t)(g * 64 + row) * MTOT + tok0 + 8 * piece);
;     LAS u32x2* vd = (LAS u32x2*)(Vl + row * 136 + piece * 16); vd[0] = (u32x2){vv.x, vv.y}; vd[1] = (u32x2){vv.z, vv.w};
	v_add_f32_e32 v50, v50, v51
	ds_bpermute_b32 v51, v181, v50
	s_waitcnt lgkmcnt(0)
	v_add_f32_e32 v50, v50, v51
	ds_bpermute_b32 v51, v182, v50
	s_waitcnt lgkmcnt(0)
	v_add_f32_e32 v50, v50, v51
	v_fmamk_f32 v50, v50, 0x3c800000, v197
	v_cmp_gt_f32_e32 vcc, s2, v50
	v_mul_f32_e32 v51, 0x4b800000, v50
	s_nop 0
	v_cndmask_b32_e32 v50, v50, v51, vcc
	v_rsq_f32_e32 v50, v50
	s_nop 0
	v_mul_f32_e32 v51, 0x45800000, v50
	v_cndmask_b32_e32 v50, v50, v51, vcc
	v_mul_f32_e32 v53, v40, v50
	v_mul_f32_e32 v45, v53, v45
	v_mul_f32_e32 v53, v36, v50
	v_mul_f32_e32 v51, v38, v50
	v_mul_f32_e32 v52, v39, v50
	v_mul_f32_e32 v47, v53, v47
	v_mul_f32_e32 v53, v41, v50
	v_mul_f32_e32 v48, v51, v48
	v_mul_f32_e32 v51, v34, v50
	v_mul_f32_e32 v49, v52, v49
	v_mul_f32_e32 v52, v35, v50
	v_mul_f32_e32 v53, v53, v44
	v_mul_f32_e32 v44, v37, v50
	v_mul_f32_e32 v51, v51, v55
	v_mul_f32_e32 v52, v52, v54
	v_mul_f32_e32 v50, v44, v46
	v_cvt_pk_bf16_f32 v44, v48, v49
	v_cvt_pk_bf16_f32 v45, v45, v53
	v_cvt_pk_bf16_f32 v46, v51, v52
	v_cvt_pk_bf16_f32 v47, v47, v50
	ds_write_b128 v107, v[44:47] offset:18432
	s_nop 0
	s_waitcnt vmcnt(2)
	ds_write2_b64 v116, v[226:227], v[228:229] offset1:1
	v_mov_b64_e32 v[44:45], v[242:243]
	v_mov_b64_e32 v[46:47], v[244:245]
	v_lshlrev_b32_e32 v48, 16, v44
	v_and_b32_e32 v49, 0xffff0000, v44
	v_pk_mul_f32 v[50:51], v[48:49], v[48:49]
	v_and_b32_e32 v44, 0xffff0000, v45
	v_lshlrev_b32_e32 v45, 16, v45
	v_pk_mul_f32 v[52:53], v[44:45], v[44:45]
	v_add_f32_e32 v50, v50, v51
	v_and_b32_e32 v54, 0xffff0000, v46
	v_lshlrev_b32_e32 v55, 16, v46
	v_add_f32_e32 v50, v53, v50
	v_pk_mul_f32 v[56:57], v[54:55], v[54:55]
	v_add_f32_e32 v50, v52, v50
	v_and_b32_e32 v46, 0xffff0000, v47
	v_lshlrev_b32_e32 v47, 16, v47
	v_add_f32_e32 v50, v57, v50
	v_pk_mul_f32 v[58:59], v[46:47], v[46:47]
	v_add_f32_e32 v50, v56, v50
	v_add_f32_e32 v50, v59, v50
	v_add_f32_e32 v50, v58, v50
	ds_bpermute_b32 v51, v180, v50
	s_waitcnt lgkmcnt(0)
	v_add_f32_e32 v50, v50, v51
	ds_bpermute_b32 v51, v181, v50
	s_waitcnt lgkmcnt(0)
	v_add_f32_e32 v50, v50, v51
	ds_bpermute_b32 v51, v182, v50
	s_waitcnt lgkmcnt(0)
	v_add_f32_e32 v50, v50, v51
	v_fmamk_f32 v50, v50, 0x3c800000, v197
	v_cmp_gt_f32_e32 vcc, s2, v50
	v_mul_f32_e32 v51, 0x4b800000, v50
	s_nop 0
	v_cndmask_b32_e32 v50, v50, v51, vcc
	v_rsq_f32_e32 v50, v50
	s_nop 0
	v_mul_f32_e32 v51, 0x45800000, v50
	v_cndmask_b32_e32 v50, v50, v51, vcc
	v_mul_f32_e32 v38, v38, v50
	v_mul_f32_e32 v34, v34, v50
	v_mul_f32_e32 v35, v35, v50
	v_mul_f32_e32 v36, v36, v50
	v_mul_f32_e32 v38, v38, v48
	v_mul_f32_e32 v48, v34, v55
	v_mul_f32_e32 v34, v39, v50
	v_mul_f32_e32 v39, v35, v54
	v_mul_f32_e32 v35, v40, v50
	v_mul_f32_e32 v40, v36, v47
	v_mul_f32_e32 v36, v41, v50
	v_mul_f32_e32 v37, v37, v50
	v_mul_f32_e32 v34, v34, v49
	v_mul_f32_e32 v35, v35, v45
	v_mul_f32_e32 v36, v36, v44
	v_mul_f32_e32 v37, v37, v46
	v_cvt_pk_bf16_f32 v34, v38, v34
	v_cvt_pk_bf16_f32 v35, v35, v36
	v_cvt_pk_bf16_f32 v36, v48, v39
	v_cvt_pk_bf16_f32 v37, v40, v37
	ds_write_b128 v107, v[34:37] offset:27648
	s_nop 0
	s_waitcnt vmcnt(0)
	ds_write2_b64 v115, v[246:247], v[198:199] offset1:1
	s_waitcnt lgkmcnt(0)
	s_barrier
	ds_read_b128 v[34:37], v91
	ds_read_b128 v[38:41], v91 offset:32
	s_waitcnt lgkmcnt(1)
	v_mfma_f32_32x32x16_bf16 v[50:65], v[34:37], v[78:81], 0
	ds_read_b128 v[34:37], v91 offset:64
	ds_read_b128 v[112:115], v91 offset:4640
	s_waitcnt lgkmcnt(2)
	v_mfma_f32_32x32x16_bf16 v[50:65], v[38:41], v[74:77], v[50:65]
	s_waitcnt lgkmcnt(1)
	v_mfma_f32_32x32x16_bf16 v[50:65], v[34:37], v[70:73], v[50:65]
	ds_read_b128 v[34:37], v91 offset:96
	s_waitcnt lgkmcnt(0)
	v_mfma_f32_32x32x16_bf16 v[50:65], v[34:37], v[66:69], v[50:65]
	ds_read_b128 v[34:37], v91 offset:4608
	s_waitcnt lgkmcnt(0)
	v_mfma_f32_32x32x16_bf16 v[34:49], v[34:37], v[78:81], 0
	s_nop 8
	v_max_f32_e32 v107, v51, v51
	v_mfma_f32_32x32x16_bf16 v[34:49], v[112:115], v[74:77], v[34:49]
	ds_read_b128 v[112:115], v91 offset:4672
	s_waitcnt lgkmcnt(0)
	v_mfma_f32_32x32x16_bf16 v[34:49], v[112:115], v[70:73], v[34:49]
	ds_read_b128 v[112:115], v91 offset:4704
	s_waitcnt lgkmcnt(0)
	v_mfma_f32_32x32x16_bf16 v[34:49], v[112:115], v[66:69], v[34:49]
	v_max_f32_e32 v112, v50, v50
	v_max_f32_e32 v107, v112, v107
	v_max3_f32 v107, v107, v52, v53
	v_max3_f32 v107, v107, v54, v55
	v_max3_f32 v107, v107, v56, v57
	v_max3_f32 v107, v107, v58, v59
	v_max3_f32 v107, v107, v60, v61
	v_max3_f32 v107, v107, v62, v63
	v_max3_f32 v107, v107, v64, v65
	s_nop 2
	v_max3_f32 v107, v107, v34, v35
	v_max3_f32 v107, v107, v36, v37
	v_max3_f32 v107, v107, v38, v39
	v_max3_f32 v107, v107, v40, v41
	v_max3_f32 v107, v107, v42, v43
	v_max3_f32 v107, v107, v44, v45
	v_max3_f32 v107, v107, v46, v47
	v_max3_f32 v107, v107, v48, v49
	ds_bpermute_b32 v112, v177, v107
	s_waitcnt lgkmcnt(0)
; #define LAS __attribute__((address_space(3)))
; __device__ __forceinline__ unsigned pk2(float lo, float hi) { unsigned r; asm("v_cvt_pk_bf16_f32 %0, %1, %2" : "=v"(r) : "v"(lo), "v"(hi)); return r; }
; __device__ __forceinline__ void attn_chunk(LAS unsigned char* Kl, LAS unsigned char* Vl, const bf16x8 (&qf)[4], f32x16 (&o)[2], float& m, float& l, int q, int half, int ii, int maskmode) {
;     ...
;     float mx = s[0][0];
; #pragma unroll
;     for (int kb = 0; kb < 2; ++kb)
; #pragma unroll
;         for (int r = 0; r < 16; ++r) mx = fmaxf(mx, s[kb][r]);
;     mx = fmaxf(mx, __shfl_xor(mx, 32));
;     const float mn = fmaxf(m, mx), alpha = __expf(m - mn);
;     float ps = 0.f;
; #pragma unroll
;     for (int kb = 0; kb < 2; ++kb)
; #pragma unroll
;         for (int r = 0; r < 16; ++r) { const float p = __expf(s[kb][r] - mn); s[kb][r] = p; ps += p; }
;     l = l * alpha + ps; m = mn;
; #pragma unroll
;     for (int db = 0; db < 2; ++db)
; #pragma unroll
;         for (int r = 0; r < 16; ++r) o[db][r] *= alpha;
; #pragma unroll
;     for (int kb = 0; kb < 2; ++kb)
; #pragma unroll
;         for (int t = 0; t < 2; ++t) {
;             union { bf16x8 v; unsigned u[4]; } pf;
; #pragma unroll
;             for (int i = 0; i < 4; ++i) pf.u[i] = pk2(s[kb][8 * t + 2 * i], s[kb][8 * t + 2 * i + 1]);
; #pragma unroll
;             for (int db = 0; db < 2; ++db) {
;                 union { bf16x8 v; u32x2 h[2]; } vf;
;                 const LAS unsigned char* vp = Vl + (32 * db + q) * 136 + (32 * kb + 16 * t + 4 * half) * 2;
;                 vf.h[0] = *(const LAS u32x2*)vp; vf.h[1] = *(const LAS u32x2*)(vp + 16);
;                 o[db] = __builtin_amdgcn_mfma_f32_32x32x16_bf16(vf.v, pf.v, o[db], 0, 0, 0);
;             }
;         }
	v_max3_f32 v113, v118, v107, v112
	v_sub_f32_e32 v34, v34, v113
	v_mul_f32_e32 v34, 0x3fb8aa3b, v34
	v_exp_f32_e32 v154, v34
	v_sub_f32_e32 v34, v35, v113
	v_mul_f32_e32 v34, 0x3fb8aa3b, v34
	v_exp_f32_e32 v156, v34
	v_sub_f32_e32 v34, v36, v113
	v_mul_f32_e32 v34, 0x3fb8aa3b, v34
	v_exp_f32_e32 v124, v34
	v_sub_f32_e32 v34, v37, v113
	v_mul_f32_e32 v34, 0x3fb8aa3b, v34
	v_exp_f32_e32 v126, v34
	v_sub_f32_e32 v34, v38, v113
	v_mul_f32_e32 v34, 0x3fb8aa3b, v34
	v_exp_f32_e32 v128, v34
	v_sub_f32_e32 v34, v39, v113
	v_mul_f32_e32 v34, 0x3fb8aa3b, v34
	v_exp_f32_e32 v130, v34
	v_sub_f32_e32 v34, v40, v113
	v_mul_f32_e32 v34, 0x3fb8aa3b, v34
	v_exp_f32_e32 v132, v34
	v_sub_f32_e32 v34, v41, v113
	v_sub_f32_e32 v50, v50, v113
	v_mul_f32_e32 v34, 0x3fb8aa3b, v34
	v_mul_f32_e32 v50, 0x3fb8aa3b, v50
	v_sub_f32_e32 v51, v51, v113
	v_exp_f32_e32 v134, v34
	v_sub_f32_e32 v34, v42, v113
	v_exp_f32_e32 v50, v50
	v_mul_f32_e32 v51, 0x3fb8aa3b, v51
	v_mul_f32_e32 v34, 0x3fb8aa3b, v34
	v_exp_f32_e32 v51, v51
	v_exp_f32_e32 v136, v34
	v_sub_f32_e32 v34, v43, v113
	v_mul_f32_e32 v34, 0x3fb8aa3b, v34
	v_exp_f32_e32 v138, v34
	v_sub_f32_e32 v34, v44, v113
	v_add_f32_e32 v112, 0, v50
	v_mul_f32_e32 v34, 0x3fb8aa3b, v34
	v_add_f32_e32 v174, v51, v112
	v_exp_f32_e32 v112, v34
	v_sub_f32_e32 v34, v45, v113
	v_mul_f32_e32 v34, 0x3fb8aa3b, v34
	v_exp_f32_e32 v114, v34
	v_sub_f32_e32 v34, v46, v113
	v_sub_f32_e32 v52, v52, v113
	v_mul_f32_e32 v34, 0x3fb8aa3b, v34
	v_mul_f32_e32 v52, 0x3fb8aa3b, v52
	v_exp_f32_e32 v116, v34
	v_sub_f32_e32 v34, v47, v113
	v_exp_f32_e32 v158, v52
	v_sub_f32_e32 v52, v53, v113
	v_mul_f32_e32 v34, 0x3fb8aa3b, v34
	v_sub_f32_e32 v107, v118, v113
	v_mul_f32_e32 v52, 0x3fb8aa3b, v52
	v_exp_f32_e32 v118, v34
	v_sub_f32_e32 v34, v48, v113
	v_exp_f32_e32 v160, v52
	v_sub_f32_e32 v52, v54, v113
	v_mul_f32_e32 v34, 0x3fb8aa3b, v34
	v_mul_f32_e32 v52, 0x3fb8aa3b, v52
	v_exp_f32_e32 v120, v34
	v_sub_f32_e32 v34, v49, v113
	v_mul_f32_e32 v107, 0x3fb8aa3b, v107
	v_exp_f32_e32 v162, v52
	v_sub_f32_e32 v52, v55, v113
	v_mul_f32_e32 v34, 0x3fb8aa3b, v34
	v_mul_f32_e32 v52, 0x3fb8aa3b, v52
	v_exp_f32_e32 v122, v34
	v_exp_f32_e32 v34, v107
	v_exp_f32_e32 v164, v52
	v_sub_f32_e32 v52, v56, v113
	ds_read2_b64 v[38:41], v119 offset0:128 offset1:130
	ds_read2_b64 v[42:45], v119 offset0:132 offset1:134
	v_mul_f32_e32 v52, 0x3fb8aa3b, v52
	v_exp_f32_e32 v166, v52
	v_sub_f32_e32 v52, v57, v113
	v_mul_f32_e32 v52, 0x3fb8aa3b, v52
	v_pk_mul_f32 v[18:19], v[18:19], v[34:35] op_sel_hi:[1,0]
	v_pk_mul_f32 v[20:21], v[20:21], v[34:35] op_sel_hi:[1,0]
	v_pk_mul_f32 v[22:23], v[22:23], v[34:35] op_sel_hi:[1,0]
	v_pk_mul_f32 v[24:25], v[24:25], v[34:35] op_sel_hi:[1,0]
	v_pk_mul_f32 v[26:27], v[26:27], v[34:35] op_sel_hi:[1,0]
	v_pk_mul_f32 v[28:29], v[28:29], v[34:35] op_sel_hi:[1,0]
	v_pk_mul_f32 v[30:31], v[30:31], v[34:35] op_sel_hi:[1,0]
	v_pk_mul_f32 v[32:33], v[32:33], v[34:35] op_sel_hi:[1,0]
	v_exp_f32_e32 v168, v52
	v_mul_f32_e32 v140, v121, v34
	v_pk_mul_f32 v[2:3], v[2:3], v[34:35] op_sel_hi:[1,0]
	v_pk_mul_f32 v[4:5], v[4:5], v[34:35] op_sel_hi:[1,0]
	v_pk_mul_f32 v[6:7], v[6:7], v[34:35] op_sel_hi:[1,0]
	v_pk_mul_f32 v[8:9], v[8:9], v[34:35] op_sel_hi:[1,0]
	v_pk_mul_f32 v[10:11], v[10:11], v[34:35] op_sel_hi:[1,0]
	v_pk_mul_f32 v[12:13], v[12:13], v[34:35] op_sel_hi:[1,0]
	v_pk_mul_f32 v[14:15], v[14:15], v[34:35] op_sel_hi:[1,0]
	v_pk_mul_f32 v[16:17], v[16:17], v[34:35] op_sel_hi:[1,0]
	v_cvt_pk_bf16_f32 v34, v50, v51
	v_cvt_pk_bf16_f32 v35, v158, v160
	v_cvt_pk_bf16_f32 v36, v162, v164
	v_cvt_pk_bf16_f32 v37, v166, v168
	v_sub_f32_e32 v52, v58, v113
	s_waitcnt lgkmcnt(1)
	v_mfma_f32_32x32x16_bf16 v[18:33], v[38:41], v[34:37], v[18:33]
	ds_read2_b64 v[38:41], v117 offset0:160 offset1:162
	v_mul_f32_e32 v52, 0x3fb8aa3b, v52
	v_exp_f32_e32 v170, v52
	v_sub_f32_e32 v52, v59, v113
	v_mul_f32_e32 v52, 0x3fb8aa3b, v52
	v_exp_f32_e32 v172, v52
	v_sub_f32_e32 v52, v60, v113
	v_mul_f32_e32 v52, 0x3fb8aa3b, v52
	v_exp_f32_e32 v142, v52
	v_sub_f32_e32 v52, v61, v113
	v_mul_f32_e32 v52, 0x3fb8aa3b, v52
	s_waitcnt lgkmcnt(0)
	v_mfma_f32_32x32x16_bf16 v[2:17], v[38:41], v[34:37], v[2:17]
	ds_read2_b64 v[38:41], v117 offset0:164 offset1:166
	v_exp_f32_e32 v144, v52
	v_sub_f32_e32 v52, v62, v113
	v_mul_f32_e32 v52, 0x3fb8aa3b, v52
	v_exp_f32_e32 v146, v52
	v_sub_f32_e32 v52, v63, v113
	v_mul_f32_e32 v52, 0x3fb8aa3b, v52
	v_exp_f32_e32 v148, v52
	v_sub_f32_e32 v52, v64, v113
	v_mul_f32_e32 v52, 0x3fb8aa3b, v52
	v_exp_f32_e32 v150, v52
	v_sub_f32_e32 v52, v65, v113
	v_mul_f32_e32 v52, 0x3fb8aa3b, v52
	v_exp_f32_e32 v152, v52
	v_cvt_pk_bf16_f32 v34, v170, v172
	v_cvt_pk_bf16_f32 v35, v142, v144
	v_cvt_pk_bf16_f32 v36, v146, v148
	v_cvt_pk_bf16_f32 v37, v150, v152
	ds_read_b128 v[218:221], v91 offset:13856
	s_waitcnt lgkmcnt(1)
	v_mfma_f32_32x32x16_bf16 v[2:17], v[38:41], v[34:37], v[2:17]
	ds_read2_b64 v[38:41], v119 offset0:136 offset1:138
	v_mfma_f32_32x32x16_bf16 v[18:33], v[42:45], v[34:37], v[18:33]
	v_cvt_pk_bf16_f32 v34, v154, v156
	v_cvt_pk_bf16_f32 v35, v124, v126
	v_cvt_pk_bf16_f32 v36, v128, v130
	v_cvt_pk_bf16_f32 v37, v132, v134
	s_waitcnt lgkmcnt(0)
	v_mfma_f32_32x32x16_bf16 v[18:33], v[38:41], v[34:37], v[18:33]
	ds_read2_b64 v[38:41], v117 offset0:168 offset1:170
	s_waitcnt lgkmcnt(0)
	v_mfma_f32_32x32x16_bf16 v[2:17], v[38:41], v[34:37], v[2:17]
	ds_read2_b64 v[38:41], v119 offset0:140 offset1:142
	v_cvt_pk_bf16_f32 v34, v136, v138
	v_cvt_pk_bf16_f32 v35, v112, v114
	v_cvt_pk_bf16_f32 v36, v116, v118
	v_cvt_pk_bf16_f32 v37, v120, v122
	s_waitcnt lgkmcnt(0)
	v_mfma_f32_32x32x16_bf16 v[18:33], v[38:41], v[34:37], v[18:33]
	ds_read2_b64 v[38:41], v117 offset0:172 offset1:174
	s_waitcnt lgkmcnt(0)
; #define LAS __attribute__((address_space(3)))
; __device__ __forceinline__ void attn_chunk(LAS unsigned char* Kl, LAS unsigned char* Vl, const bf16x8 (&qf)[4], f32x16 (&o)[2], float& m, float& l, int q, int half, int ii, int maskmode) {
;     ...
;     for (int kb = 0; kb < 2; ++kb) {
; #pragma unroll
;         for (int r = 0; r < 16; ++r) s[kb][r] = 0.f;
; #pragma unroll
;         for (int ks = 0; ks < 4; ++ks) { const bf16x8 kf = *(const LAS bf16x8*)(Kl + (32 * kb + q) * 144 + (2 * ks + half) * 16); s[kb] = __builtin_amdgcn_mfma_f32_32x32x16_bf16(kf, qf[ks], s[kb], 0, 0, 0); }
;     }
;     if (maskmode != 0) {
; #pragma unroll
;         for (int kb = 0; kb < 2; ++kb)
; #pragma unroll
;             for (int r = 0; r < 16; ++r) { const int jj = 32 * kb + 8 * (r >> 2) + 4 * half + (r & 3); const bool ok = (maskmode == 1) ? (jj >= ii) : (jj <= ii); if (!ok) s[kb][r] = -1e30f; }
;     }
;     float mx = s[0][0];
; #pragma unroll
;     for (int kb = 0; kb < 2; ++kb)
; #pragma unroll
;         for (int r = 0; r < 16; ++r) mx = fmaxf(mx, s[kb][r]);
;     mx = fmaxf(mx, __shfl_xor(mx, 32));
;     const float mn = fmaxf(m, mx), alpha = __expf(m - mn);
;     float ps = 0.f;
; #pragma unroll
;     for (int kb = 0; kb < 2; ++kb)
; #pragma unroll
;         for (int r = 0; r < 16; ++r) { const float p = __expf(s[kb][r] - mn); s[kb][r] = p; ps += p; }
	v_mfma_f32_32x32x16_bf16 v[2:17], v[38:41], v[34:37], v[2:17]
	ds_read_b128 v[34:37], v91 offset:9216
	s_waitcnt lgkmcnt(0)
	v_mfma_f32_32x32x16_bf16 v[50:65], v[34:37], v[78:81], 0
	ds_read_b128 v[34:37], v91 offset:9248
	s_waitcnt lgkmcnt(0)
	v_mfma_f32_32x32x16_bf16 v[50:65], v[34:37], v[74:77], v[50:65]
	ds_read_b128 v[34:37], v91 offset:9280
	s_waitcnt lgkmcnt(0)
	v_mfma_f32_32x32x16_bf16 v[50:65], v[34:37], v[70:73], v[50:65]
	ds_read_b128 v[34:37], v91 offset:9312
	s_waitcnt lgkmcnt(0)
	v_mfma_f32_32x32x16_bf16 v[50:65], v[34:37], v[66:69], v[50:65]
	ds_read_b128 v[34:37], v91 offset:13824
	s_waitcnt lgkmcnt(0)
	v_mfma_f32_32x32x16_bf16 v[34:49], v[34:37], v[78:81], 0
	s_nop 8
	v_max_f32_e32 v107, v51, v51
	v_max_f32_e32 v115, v50, v50
	v_max_f32_e32 v107, v115, v107
	v_max3_f32 v107, v107, v52, v53
	v_max3_f32 v107, v107, v54, v55
	v_max3_f32 v107, v107, v56, v57
	v_max3_f32 v107, v107, v58, v59
	v_mfma_f32_32x32x16_bf16 v[34:49], v[218:221], v[74:77], v[34:49]
	ds_read_b128 v[218:221], v91 offset:13888
	v_max3_f32 v107, v107, v60, v61
	v_max3_f32 v107, v107, v62, v63
	v_max3_f32 v107, v107, v64, v65
	s_waitcnt lgkmcnt(0)
	v_mfma_f32_32x32x16_bf16 v[34:49], v[218:221], v[70:73], v[34:49]
	ds_read_b128 v[218:221], v91 offset:13920
	s_waitcnt lgkmcnt(0)
	v_mfma_f32_32x32x16_bf16 v[34:49], v[218:221], v[66:69], v[34:49]
	s_nop 11
	v_max3_f32 v107, v107, v34, v35
	v_max3_f32 v107, v107, v36, v37
	v_max3_f32 v107, v107, v38, v39
	v_max3_f32 v107, v107, v40, v41
	v_max3_f32 v107, v107, v42, v43
	v_max3_f32 v107, v107, v44, v45
	v_max3_f32 v107, v107, v46, v47
	v_max3_f32 v107, v107, v48, v49
	ds_bpermute_b32 v115, v177, v107
	s_waitcnt lgkmcnt(0)
	v_max3_f32 v107, v113, v107, v115
	v_sub_f32_e32 v50, v50, v107
	v_mul_f32_e32 v50, 0x3fb8aa3b, v50
	v_exp_f32_e32 v159, v50
	v_sub_f32_e32 v50, v51, v107
	v_mul_f32_e32 v50, 0x3fb8aa3b, v50
	v_exp_f32_e32 v161, v50
	v_sub_f32_e32 v50, v52, v107
	v_mul_f32_e32 v50, 0x3fb8aa3b, v50
	v_exp_f32_e32 v163, v50
	v_sub_f32_e32 v50, v53, v107
	v_mul_f32_e32 v50, 0x3fb8aa3b, v50
	v_exp_f32_e32 v165, v50
	v_sub_f32_e32 v50, v54, v107
	v_mul_f32_e32 v50, 0x3fb8aa3b, v50
	v_exp_f32_e32 v167, v50
	v_sub_f32_e32 v50, v55, v107
	v_mul_f32_e32 v50, 0x3fb8aa3b, v50
	v_exp_f32_e32 v169, v50
	v_sub_f32_e32 v50, v56, v107
	v_mul_f32_e32 v50, 0x3fb8aa3b, v50
	v_exp_f32_e32 v171, v50
	v_sub_f32_e32 v50, v57, v107
	v_mul_f32_e32 v50, 0x3fb8aa3b, v50
	v_sub_f32_e32 v52, v59, v107
	v_exp_f32_e32 v173, v50
	v_sub_f32_e32 v50, v58, v107
	v_mul_f32_e32 v52, 0x3fb8aa3b, v52
	v_mul_f32_e32 v50, 0x3fb8aa3b, v50
	v_exp_f32_e32 v145, v52
	v_sub_f32_e32 v52, v60, v107
	v_sub_f32_e32 v34, v34, v107
	v_exp_f32_e32 v143, v50
	v_pk_add_f32 v[50:51], v[158:159], v[174:175]
	v_mul_f32_e32 v52, 0x3fb8aa3b, v52
	v_mul_f32_e32 v34, 0x3fb8aa3b, v34
	v_pk_add_f32 v[50:51], v[160:161], v[50:51]
	v_exp_f32_e32 v147, v52
	v_sub_f32_e32 v52, v61, v107
	v_exp_f32_e32 v125, v34
	v_sub_f32_e32 v34, v35, v107
	v_pk_add_f32 v[50:51], v[162:163], v[50:51]
	v_mul_f32_e32 v52, 0x3fb8aa3b, v52
	v_mul_f32_e32 v34, 0x3fb8aa3b, v34
	v_pk_add_f32 v[50:51], v[164:165], v[50:51]
	v_exp_f32_e32 v149, v52
	v_sub_f32_e32 v52, v62, v107
	v_exp_f32_e32 v127, v34
	v_sub_f32_e32 v34, v36, v107
	v_sub_f32_e32 v36, v38, v107
	v_pk_add_f32 v[50:51], v[166:167], v[50:51]
	v_mul_f32_e32 v52, 0x3fb8aa3b, v52
	v_mul_f32_e32 v36, 0x3fb8aa3b, v36
	v_pk_add_f32 v[50:51], v[168:169], v[50:51]
	v_exp_f32_e32 v151, v52
	v_sub_f32_e32 v52, v63, v107
	v_exp_f32_e32 v133, v36
	v_sub_f32_e32 v36, v39, v107
	v_pk_add_f32 v[50:51], v[170:171], v[50:51]
	v_mul_f32_e32 v52, 0x3fb8aa3b, v52
	v_mul_f32_e32 v34, 0x3fb8aa3b, v34
	v_mul_f32_e32 v36, 0x3fb8aa3b, v36
	v_pk_add_f32 v[50:51], v[172:173], v[50:51]
	v_exp_f32_e32 v153, v52
	v_sub_f32_e32 v52, v64, v107
	v_exp_f32_e32 v129, v34
	v_sub_f32_e32 v34, v37, v107
	v_exp_f32_e32 v135, v36
	v_sub_f32_e32 v36, v40, v107
	v_pk_add_f32 v[50:51], v[142:143], v[50:51]
	v_mul_f32_e32 v52, 0x3fb8aa3b, v52
	v_mul_f32_e32 v34, 0x3fb8aa3b, v34
	v_mul_f32_e32 v36, 0x3fb8aa3b, v36
	v_exp_f32_e32 v155, v52
	v_sub_f32_e32 v52, v65, v107
	v_exp_f32_e32 v131, v34
	v_pk_add_f32 v[34:35], v[144:145], v[50:51]
	v_exp_f32_e32 v137, v36
	v_sub_f32_e32 v36, v41, v107
	v_mul_f32_e32 v52, 0x3fb8aa3b, v52
	v_pk_add_f32 v[34:35], v[146:147], v[34:35]
	v_mul_f32_e32 v36, 0x3fb8aa3b, v36
	v_exp_f32_e32 v157, v52
	v_pk_add_f32 v[34:35], v[148:149], v[34:35]
	v_exp_f32_e32 v139, v36
	v_sub_f32_e32 v36, v42, v107
	v_sub_f32_e32 v113, v113, v107
	v_pk_add_f32 v[34:35], v[150:151], v[34:35]
	v_mul_f32_e32 v36, 0x3fb8aa3b, v36
	v_mul_f32_e32 v214, 0x3fb8aa3b, v113
	v_pk_add_f32 v[34:35], v[152:153], v[34:35]
	v_exp_f32_e32 v113, v36
	v_sub_f32_e32 v36, v43, v107
	v_pk_add_f32 v[34:35], v[154:155], v[34:35]
	v_mul_f32_e32 v36, 0x3fb8aa3b, v36
	v_pk_add_f32 v[34:35], v[156:157], v[34:35]
	v_exp_f32_e32 v115, v36
	v_sub_f32_e32 v36, v44, v107
	v_pk_add_f32 v[34:35], v[124:125], v[34:35]
	v_mul_f32_e32 v36, 0x3fb8aa3b, v36
	v_pk_add_f32 v[34:35], v[126:127], v[34:35]
	v_exp_f32_e32 v117, v36
	v_sub_f32_e32 v36, v45, v107
	v_pk_add_f32 v[34:35], v[128:129], v[34:35]
	v_mul_f32_e32 v36, 0x3fb8aa3b, v36
	v_pk_add_f32 v[34:35], v[130:131], v[34:35]
	v_exp_f32_e32 v119, v36
	v_sub_f32_e32 v36, v46, v107
	v_mul_f32_e32 v36, 0x3fb8aa3b, v36
	v_exp_f32_e32 v52, v214
	v_pk_add_f32 v[34:35], v[132:133], v[34:35]
	v_exp_f32_e32 v121, v36
	v_sub_f32_e32 v36, v47, v107
	v_pk_add_f32 v[34:35], v[134:135], v[34:35]
	v_mul_f32_e32 v36, 0x3fb8aa3b, v36
	v_pk_add_f32 v[34:35], v[136:137], v[34:35]
	v_exp_f32_e32 v123, v36
	v_sub_f32_e32 v36, v48, v107
	v_pk_add_f32 v[34:35], v[138:139], v[34:35]
; #define LAS __attribute__((address_space(3)))
; __device__ __forceinline__ unsigned pk2(float lo, float hi) { unsigned r; asm("v_cvt_pk_bf16_f32 %0, %1, %2" : "=v"(r) : "v"(lo), "v"(hi)); return r; }
; __device__ __forceinline__ void attn_chunk(LAS unsigned char* Kl, LAS unsigned char* Vl, const bf16x8 (&qf)[4], f32x16 (&o)[2], float& m, float& l, int q, int half, int ii, int maskmode) {
;     ...
;     l = l * alpha + ps; m = mn;
; #pragma unroll
;     for (int db = 0; db < 2; ++db)
; #pragma unroll
;         for (int r = 0; r < 16; ++r) o[db][r] *= alpha;
; #pragma unroll
;     for (int kb = 0; kb < 2; ++kb)
; #pragma unroll
;         for (int t = 0; t < 2; ++t) {
;             union { bf16x8 v; unsigned u[4]; } pf;
; #pragma unroll
;             for (int i = 0; i < 4; ++i) pf.u[i] = pk2(s[kb][8 * t + 2 * i], s[kb][8 * t + 2 * i + 1]);
; #pragma unroll
;             for (int db = 0; db < 2; ++db) {
;                 union { bf16x8 v; u32x2 h[2]; } vf;
;                 const LAS unsigned char* vp = Vl + (32 * db + q) * 136 + (32 * kb + 16 * t + 4 * half) * 2;
;                 vf.h[0] = *(const LAS u32x2*)vp; vf.h[1] = *(const LAS u32x2*)(vp + 16);
;                 o[db] = __builtin_amdgcn_mfma_f32_32x32x16_bf16(vf.v, pf.v, o[db], 0, 0, 0);
;             }
;         }
	v_mul_f32_e32 v36, 0x3fb8aa3b, v36
	v_pk_add_f32 v[34:35], v[112:113], v[34:35]
	v_pk_mul_f32 v[40:41], v[24:25], v[52:53] op_sel_hi:[1,0]
	v_pk_mul_f32 v[38:39], v[22:23], v[52:53] op_sel_hi:[1,0]
	v_pk_mul_f32 v[24:25], v[8:9], v[52:53] op_sel_hi:[1,0]
	v_pk_mul_f32 v[22:23], v[6:7], v[52:53] op_sel_hi:[1,0]
	ds_read2_b64 v[6:9], v192 offset0:192 offset1:194
	v_exp_f32_e32 v141, v36
	v_sub_f32_e32 v36, v49, v107
	v_pk_add_f32 v[34:35], v[114:115], v[34:35]
	v_mul_f32_e32 v36, 0x3fb8aa3b, v36
	v_pk_add_f32 v[34:35], v[116:117], v[34:35]
	v_exp_f32_e32 v50, v36
	v_pk_add_f32 v[34:35], v[118:119], v[34:35]
	v_pk_mul_f32 v[48:49], v[32:33], v[52:53] op_sel_hi:[1,0]
	v_pk_add_f32 v[34:35], v[120:121], v[34:35]
	v_pk_mul_f32 v[46:47], v[30:31], v[52:53] op_sel_hi:[1,0]
	v_pk_add_f32 v[34:35], v[122:123], v[34:35]
	v_pk_mul_f32 v[44:45], v[28:29], v[52:53] op_sel_hi:[1,0]
	v_pk_add_f32 v[34:35], v[140:141], v[34:35]
	v_pk_mul_f32 v[42:43], v[26:27], v[52:53] op_sel_hi:[1,0]
	v_add_f32_e32 v156, v35, v50
	v_fmac_f32_e32 v156, v34, v52
	v_pk_mul_f32 v[36:37], v[20:21], v[52:53] op_sel_hi:[1,0]
	v_pk_mul_f32 v[34:35], v[18:19], v[52:53] op_sel_hi:[1,0]
	v_pk_mul_f32 v[20:21], v[4:5], v[52:53] op_sel_hi:[1,0]
	v_pk_mul_f32 v[18:19], v[2:3], v[52:53] op_sel_hi:[1,0]
	v_cvt_pk_bf16_f32 v2, v159, v161
	v_cvt_pk_bf16_f32 v3, v163, v165
	v_cvt_pk_bf16_f32 v4, v167, v169
	v_cvt_pk_bf16_f32 v5, v171, v173
	v_pk_mul_f32 v[32:33], v[16:17], v[52:53] op_sel_hi:[1,0]
	s_waitcnt lgkmcnt(0)
	v_mfma_f32_32x32x16_bf16 v[34:49], v[6:9], v[2:5], v[34:49]
	ds_read2_b64 v[6:9], v191 offset0:224 offset1:226
	v_mul_f32_e64 v30, v14, v52
	v_mul_f32_e64 v31, v15, v52
	v_mul_f32_e64 v28, v12, v52
	v_mul_f32_e64 v29, v13, v52
	v_pk_mul_f32 v[26:27], v[10:11], v[52:53] op_sel_hi:[1,0]
	s_waitcnt lgkmcnt(0)
	s_nop 0
	v_mfma_f32_32x32x16_bf16 v[18:33], v[6:9], v[2:5], v[18:33]
	ds_read2_b64 v[6:9], v192 offset0:196 offset1:198
	v_cvt_pk_bf16_f32 v2, v143, v145
	v_cvt_pk_bf16_f32 v3, v147, v149
	v_cvt_pk_bf16_f32 v4, v151, v153
	v_cvt_pk_bf16_f32 v5, v155, v157
	s_waitcnt lgkmcnt(0)
	v_mfma_f32_32x32x16_bf16 v[34:49], v[6:9], v[2:5], v[34:49]
	ds_read2_b64 v[6:9], v191 offset0:228 offset1:230
	s_waitcnt lgkmcnt(0)
	v_mfma_f32_32x32x16_bf16 v[18:33], v[6:9], v[2:5], v[18:33]
	ds_read2_b64 v[6:9], v192 offset0:200 offset1:202
	v_cvt_pk_bf16_f32 v2, v125, v127
	v_cvt_pk_bf16_f32 v3, v129, v131
	v_cvt_pk_bf16_f32 v4, v133, v135
	v_cvt_pk_bf16_f32 v5, v137, v139
	s_waitcnt lgkmcnt(0)
	v_mfma_f32_32x32x16_bf16 v[34:49], v[6:9], v[2:5], v[34:49]
	ds_read2_b64 v[6:9], v191 offset0:232 offset1:234
	s_waitcnt lgkmcnt(0)
	v_mfma_f32_32x32x16_bf16 v[18:33], v[6:9], v[2:5], v[18:33]
	ds_read2_b64 v[6:9], v192 offset0:204 offset1:206
	v_cvt_pk_bf16_f32 v2, v113, v115
	v_cvt_pk_bf16_f32 v3, v117, v119
	v_cvt_pk_bf16_f32 v4, v121, v123
	v_cvt_pk_bf16_f32 v5, v141, v50
	ds_read_b128 v[112:115], v91 offset:23072
	s_waitcnt lgkmcnt(1)
	v_mfma_f32_32x32x16_bf16 v[34:49], v[6:9], v[2:5], v[34:49]
	ds_read2_b64 v[6:9], v191 offset0:236 offset1:238
	s_waitcnt lgkmcnt(0)
	v_mfma_f32_32x32x16_bf16 v[18:33], v[6:9], v[2:5], v[18:33]
	ds_read_b128 v[2:5], v91 offset:18432
	s_waitcnt lgkmcnt(0)
	v_mfma_f32_32x32x16_bf16 v[50:65], v[2:5], v[78:81], 0
	ds_read_b128 v[2:5], v91 offset:18464
	s_waitcnt lgkmcnt(0)
	v_mfma_f32_32x32x16_bf16 v[50:65], v[2:5], v[74:77], v[50:65]
	ds_read_b128 v[2:5], v91 offset:18496
	s_waitcnt lgkmcnt(0)
	v_mfma_f32_32x32x16_bf16 v[50:65], v[2:5], v[70:73], v[50:65]
	ds_read_b128 v[2:5], v91 offset:18528
	s_waitcnt lgkmcnt(0)
	v_mfma_f32_32x32x16_bf16 v[50:65], v[2:5], v[66:69], v[50:65]
	ds_read_b128 v[2:5], v91 offset:23040
	s_waitcnt lgkmcnt(0)
	v_mfma_f32_32x32x16_bf16 v[2:17], v[2:5], v[78:81], 0
	v_mfma_f32_32x32x16_bf16 v[2:17], v[112:115], v[74:77], v[2:17]
	ds_read_b128 v[112:115], v91 offset:23104
	s_waitcnt lgkmcnt(0)
	v_mfma_f32_32x32x16_bf16 v[2:17], v[112:115], v[70:73], v[2:17]
	ds_read_b128 v[112:115], v91 offset:23136
	s_waitcnt lgkmcnt(0)
	v_mfma_f32_32x32x16_bf16 v[2:17], v[112:115], v[66:69], v[2:17]
	s_nop 1
	v_max_f32_e32 v112, v51, v51
	v_max_f32_e32 v113, v50, v50
	v_max_f32_e32 v112, v113, v112
	v_max3_f32 v112, v112, v52, v53
	v_max3_f32 v112, v112, v54, v55
	v_max3_f32 v112, v112, v56, v57
	v_max3_f32 v112, v112, v58, v59
	v_max3_f32 v112, v112, v60, v61
	v_max3_f32 v112, v112, v62, v63
	v_max3_f32 v112, v112, v64, v65
	v_max3_f32 v112, v112, v2, v3
	v_max3_f32 v112, v112, v4, v5
	v_max3_f32 v112, v112, v6, v7
	v_max3_f32 v112, v112, v8, v9
	v_max3_f32 v112, v112, v10, v11
	v_max3_f32 v112, v112, v12, v13
	v_max3_f32 v112, v112, v14, v15
	v_max3_f32 v112, v112, v16, v17
	ds_bpermute_b32 v113, v177, v112
	s_waitcnt lgkmcnt(0)
; #define LAS __attribute__((address_space(3)))
; __device__ __forceinline__ unsigned pk2(float lo, float hi) { unsigned r; asm("v_cvt_pk_bf16_f32 %0, %1, %2" : "=v"(r) : "v"(lo), "v"(hi)); return r; }
; __device__ __forceinline__ void attn_chunk(LAS unsigned char* Kl, LAS unsigned char* Vl, const bf16x8 (&qf)[4], f32x16 (&o)[2], float& m, float& l, int q, int half, int ii, int maskmode) {
;     ...
;     float mx = s[0][0];
; #pragma unroll
;     for (int kb = 0; kb < 2; ++kb)
; #pragma unroll
;         for (int r = 0; r < 16; ++r) mx = fmaxf(mx, s[kb][r]);
;     mx = fmaxf(mx, __shfl_xor(mx, 32));
;     const float mn = fmaxf(m, mx), alpha = __expf(m - mn);
;     float ps = 0.f;
; #pragma unroll
;     for (int kb = 0; kb < 2; ++kb)
; #pragma unroll
;         for (int r = 0; r < 16; ++r) { const float p = __expf(s[kb][r] - mn); s[kb][r] = p; ps += p; }
;     l = l * alpha + ps; m = mn;
; #pragma unroll
;     for (int db = 0; db < 2; ++db)
; #pragma unroll
;         for (int r = 0; r < 16; ++r) o[db][r] *= alpha;
; #pragma unroll
;     for (int kb = 0; kb < 2; ++kb)
; #pragma unroll
;         for (int t = 0; t < 2; ++t) {
;             union { bf16x8 v; unsigned u[4]; } pf;
; #pragma unroll
;             for (int i = 0; i < 4; ++i) pf.u[i] = pk2(s[kb][8 * t + 2 * i], s[kb][8 * t + 2 * i + 1]);
; #pragma unroll
;             for (int db = 0; db < 2; ++db) {
;                 union { bf16x8 v; u32x2 h[2]; } vf;
;                 const LAS unsigned char* vp = Vl + (32 * db + q) * 136 + (32 * kb + 16 * t + 4 * half) * 2;
;                 vf.h[0] = *(const LAS u32x2*)vp; vf.h[1] = *(const LAS u32x2*)(vp + 16);
;                 o[db] = __builtin_amdgcn_mfma_f32_32x32x16_bf16(vf.v, pf.v, o[db], 0, 0, 0);
;             }
;         }
	v_max3_f32 v113, v107, v112, v113
	v_sub_f32_e32 v50, v50, v113
	v_mul_f32_e32 v50, 0x3fb8aa3b, v50
	v_sub_f32_e32 v51, v51, v113
	v_exp_f32_e32 v115, v50
	v_mul_f32_e32 v51, 0x3fb8aa3b, v51
	v_exp_f32_e32 v51, v51
	v_sub_f32_e32 v2, v2, v113
	v_add_f32_e32 v50, 0, v115
	v_mul_f32_e32 v2, 0x3fb8aa3b, v2
	v_add_f32_e32 v174, v51, v50
	v_sub_f32_e32 v50, v52, v113
	v_mul_f32_e32 v50, 0x3fb8aa3b, v50
	v_exp_f32_e32 v158, v50
	v_sub_f32_e32 v50, v53, v113
	v_mul_f32_e32 v50, 0x3fb8aa3b, v50
	v_exp_f32_e32 v160, v50
	v_sub_f32_e32 v50, v54, v113
	v_mul_f32_e32 v50, 0x3fb8aa3b, v50
	v_exp_f32_e32 v162, v50
	v_sub_f32_e32 v50, v55, v113
	v_mul_f32_e32 v50, 0x3fb8aa3b, v50
	v_exp_f32_e32 v164, v50
	v_sub_f32_e32 v50, v56, v113
	v_mul_f32_e32 v50, 0x3fb8aa3b, v50
	v_exp_f32_e32 v166, v50
	v_sub_f32_e32 v50, v57, v113
	v_exp_f32_e32 v146, v2
	v_sub_f32_e32 v2, v3, v113
	v_mul_f32_e32 v50, 0x3fb8aa3b, v50
	v_mul_f32_e32 v2, 0x3fb8aa3b, v2
	v_exp_f32_e32 v168, v50
	v_sub_f32_e32 v50, v58, v113
	v_exp_f32_e32 v150, v2
	v_sub_f32_e32 v2, v4, v113
	v_mul_f32_e32 v50, 0x3fb8aa3b, v50
	v_mul_f32_e32 v2, 0x3fb8aa3b, v2
	v_exp_f32_e32 v170, v50
	v_sub_f32_e32 v50, v59, v113
	v_exp_f32_e32 v128, v2
	v_sub_f32_e32 v2, v5, v113
	v_mul_f32_e32 v50, 0x3fb8aa3b, v50
	v_mul_f32_e32 v2, 0x3fb8aa3b, v2
	v_exp_f32_e32 v172, v50
	v_sub_f32_e32 v50, v60, v113
	v_exp_f32_e32 v132, v2
	v_sub_f32_e32 v2, v6, v113
	v_mul_f32_e32 v50, 0x3fb8aa3b, v50
	v_mul_f32_e32 v2, 0x3fb8aa3b, v2
	v_exp_f32_e32 v124, v50
	v_sub_f32_e32 v50, v61, v113
	v_exp_f32_e32 v136, v2
	v_sub_f32_e32 v2, v7, v113
	v_mul_f32_e32 v50, 0x3fb8aa3b, v50
	v_mul_f32_e32 v2, 0x3fb8aa3b, v2
	v_exp_f32_e32 v126, v50
	v_sub_f32_e32 v50, v62, v113
	v_exp_f32_e32 v140, v2
	v_sub_f32_e32 v2, v8, v113
	v_mul_f32_e32 v50, 0x3fb8aa3b, v50
	v_mul_f32_e32 v2, 0x3fb8aa3b, v2
	v_exp_f32_e32 v130, v50
	v_sub_f32_e32 v50, v63, v113
	v_exp_f32_e32 v144, v2
	v_sub_f32_e32 v2, v9, v113
	v_mul_f32_e32 v50, 0x3fb8aa3b, v50
	v_mul_f32_e32 v2, 0x3fb8aa3b, v2
	v_exp_f32_e32 v134, v50
	v_sub_f32_e32 v50, v64, v113
	v_exp_f32_e32 v148, v2
	v_sub_f32_e32 v2, v10, v113
	v_mul_f32_e32 v50, 0x3fb8aa3b, v50
	v_mul_f32_e32 v2, 0x3fb8aa3b, v2
	v_sub_f32_e32 v107, v107, v113
	v_exp_f32_e32 v138, v50
	v_sub_f32_e32 v50, v65, v113
	v_exp_f32_e32 v152, v2
	v_sub_f32_e32 v2, v11, v113
	v_mul_f32_e32 v107, 0x3fb8aa3b, v107
	v_mul_f32_e32 v50, 0x3fb8aa3b, v50
	v_mul_f32_e32 v2, 0x3fb8aa3b, v2
	v_exp_f32_e32 v142, v50
	v_exp_f32_e32 v154, v2
	v_sub_f32_e32 v2, v12, v113
	v_exp_f32_e32 v50, v107
	v_mul_f32_e32 v2, 0x3fb8aa3b, v2
	v_exp_f32_e32 v112, v2
	v_sub_f32_e32 v2, v13, v113
	v_mul_f32_e32 v2, 0x3fb8aa3b, v2
	v_exp_f32_e32 v114, v2
	v_sub_f32_e32 v2, v14, v113
	v_pk_mul_f32 v[8:9], v[40:41], v[50:51] op_sel_hi:[1,0]
	v_pk_mul_f32 v[6:7], v[38:39], v[50:51] op_sel_hi:[1,0]
	ds_read2_b64 v[38:41], v194 offset1:2
	v_mul_f32_e32 v2, 0x3fb8aa3b, v2
	v_exp_f32_e32 v116, v2
	v_sub_f32_e32 v2, v15, v113
	v_mul_f32_e32 v2, 0x3fb8aa3b, v2
	v_exp_f32_e32 v118, v2
	v_sub_f32_e32 v2, v16, v113
	v_mul_f32_e32 v2, 0x3fb8aa3b, v2
	v_exp_f32_e32 v120, v2
	v_sub_f32_e32 v2, v17, v113
	v_mul_f32_e32 v2, 0x3fb8aa3b, v2
	v_exp_f32_e32 v122, v2
	v_pk_mul_f32 v[16:17], v[48:49], v[50:51] op_sel_hi:[1,0]
	v_pk_mul_f32 v[14:15], v[46:47], v[50:51] op_sel_hi:[1,0]
	v_pk_mul_f32 v[12:13], v[44:45], v[50:51] op_sel_hi:[1,0]
	v_pk_mul_f32 v[10:11], v[42:43], v[50:51] op_sel_hi:[1,0]
	v_pk_mul_f32 v[4:5], v[36:37], v[50:51] op_sel_hi:[1,0]
	v_pk_mul_f32 v[2:3], v[34:35], v[50:51] op_sel_hi:[1,0]
	v_cvt_pk_bf16_f32 v34, v115, v51
	v_cvt_pk_bf16_f32 v35, v158, v160
	v_cvt_pk_bf16_f32 v36, v162, v164
	v_cvt_pk_bf16_f32 v37, v166, v168
	v_pk_mul_f32 v[32:33], v[32:33], v[50:51] op_sel_hi:[1,0]
	s_waitcnt lgkmcnt(0)
	v_mfma_f32_32x32x16_bf16 v[2:17], v[38:41], v[34:37], v[2:17]
	ds_read2_b64 v[38:41], v193 offset1:2
	ds_read2_b64 v[42:45], v193 offset0:4 offset1:6
	v_mul_f32_e64 v30, v30, v50
	v_mul_f32_e64 v31, v31, v50
	v_mul_f32_e64 v28, v28, v50
	v_mul_f32_e64 v29, v29, v50
	v_pk_mul_f32 v[26:27], v[26:27], v[50:51] op_sel_hi:[1,0]
	v_pk_mul_f32 v[24:25], v[24:25], v[50:51] op_sel_hi:[1,0]
	v_pk_mul_f32 v[22:23], v[22:23], v[50:51] op_sel_hi:[1,0]
	v_pk_mul_f32 v[20:21], v[20:21], v[50:51] op_sel_hi:[1,0]
	v_pk_mul_f32 v[18:19], v[18:19], v[50:51] op_sel_hi:[1,0]
	v_mul_f32_e32 v156, v156, v50
	v_mov_b32_e32 v107, v1
	s_waitcnt lgkmcnt(1)
	v_mfma_f32_32x32x16_bf16 v[18:33], v[38:41], v[34:37], v[18:33]
	ds_read2_b64 v[38:41], v194 offset0:4 offset1:6
	v_cvt_pk_bf16_f32 v34, v170, v172
	v_cvt_pk_bf16_f32 v35, v124, v126
	v_cvt_pk_bf16_f32 v36, v130, v134
	v_cvt_pk_bf16_f32 v37, v138, v142
	s_waitcnt lgkmcnt(0)
	v_mfma_f32_32x32x16_bf16 v[2:17], v[38:41], v[34:37], v[2:17]
	ds_read2_b64 v[38:41], v194 offset0:8 offset1:10
	v_mfma_f32_32x32x16_bf16 v[18:33], v[42:45], v[34:37], v[18:33]
	v_cvt_pk_bf16_f32 v34, v146, v150
	v_cvt_pk_bf16_f32 v35, v128, v132
	v_cvt_pk_bf16_f32 v36, v136, v140
	v_cvt_pk_bf16_f32 v37, v144, v148
	s_waitcnt lgkmcnt(0)
	v_mfma_f32_32x32x16_bf16 v[2:17], v[38:41], v[34:37], v[2:17]
	ds_read2_b64 v[38:41], v193 offset0:8 offset1:10
	s_waitcnt lgkmcnt(0)
	v_mfma_f32_32x32x16_bf16 v[18:33], v[38:41], v[34:37], v[18:33]
	ds_read2_b64 v[38:41], v194 offset0:12 offset1:14
	v_cvt_pk_bf16_f32 v34, v152, v154
	v_cvt_pk_bf16_f32 v35, v112, v114
	v_cvt_pk_bf16_f32 v36, v116, v118
	v_cvt_pk_bf16_f32 v37, v120, v122
	s_waitcnt lgkmcnt(0)
	v_mfma_f32_32x32x16_bf16 v[2:17], v[38:41], v[34:37], v[2:17]
	ds_read2_b64 v[38:41], v193 offset0:12 offset1:14
	s_waitcnt lgkmcnt(0)
	v_mfma_f32_32x32x16_bf16 v[18:33], v[38:41], v[34:37], v[18:33]
	ds_read_b128 v[34:37], v91 offset:27648
	s_waitcnt lgkmcnt(0)
; #define LAS __attribute__((address_space(3)))
; __device__ __forceinline__ void attn_chunk(LAS unsigned char* Kl, LAS unsigned char* Vl, const bf16x8 (&qf)[4], f32x16 (&o)[2], float& m, float& l, int q, int half, int ii, int maskmode) {
;     ...
;     for (int kb = 0; kb < 2; ++kb) {
; #pragma unroll
;         for (int r = 0; r < 16; ++r) s[kb][r] = 0.f;
; #pragma unroll
;         for (int ks = 0; ks < 4; ++ks) { const bf16x8 kf = *(const LAS bf16x8*)(Kl + (32 * kb + q) * 144 + (2 * ks + half) * 16); s[kb] = __builtin_amdgcn_mfma_f32_32x32x16_bf16(kf, qf[ks], s[kb], 0, 0, 0); }
;     }
;     if (maskmode != 0) {
; #pragma unroll
;         for (int kb = 0; kb < 2; ++kb)
; #pragma unroll
;             for (int r = 0; r < 16; ++r) { const int jj = 32 * kb + 8 * (r >> 2) + 4 * half + (r & 3); const bool ok = (maskmode == 1) ? (jj >= ii) : (jj <= ii); if (!ok) s[kb][r] = -1e30f; }
;     }
;     float mx = s[0][0];
; #pragma unroll
;     for (int kb = 0; kb < 2; ++kb)
; #pragma unroll
;         for (int r = 0; r < 16; ++r) mx = fmaxf(mx, s[kb][r]);
;     mx = fmaxf(mx, __shfl_xor(mx, 32));
;     const float mn = fmaxf(m, mx), alpha = __expf(m - mn);
;     float ps = 0.f;
; #pragma unroll
;     for (int kb = 0; kb < 2; ++kb)
; #pragma unroll
;         for (int r = 0; r < 16; ++r) { const float p = __expf(s[kb][r] - mn); s[kb][r] = p; ps += p; }
;     l = l * alpha + ps; m = mn;
	v_mfma_f32_32x32x16_bf16 v[50:65], v[34:37], v[78:81], 0
	ds_read_b128 v[34:37], v91 offset:27680
	s_waitcnt lgkmcnt(0)
	v_mfma_f32_32x32x16_bf16 v[50:65], v[34:37], v[74:77], v[50:65]
	ds_read_b128 v[34:37], v91 offset:27712
	s_waitcnt lgkmcnt(0)
	v_mfma_f32_32x32x16_bf16 v[50:65], v[34:37], v[70:73], v[50:65]
	ds_read_b128 v[34:37], v91 offset:27744
	s_waitcnt lgkmcnt(0)
	v_mfma_f32_32x32x16_bf16 v[50:65], v[34:37], v[66:69], v[50:65]
	ds_read_b128 v[34:37], v91 offset:32256
	s_waitcnt lgkmcnt(0)
	v_mfma_f32_32x32x16_bf16 v[34:49], v[34:37], v[78:81], 0
	ds_read_b128 v[78:81], v91 offset:32288
	s_waitcnt lgkmcnt(0)
	v_mfma_f32_32x32x16_bf16 v[34:49], v[78:81], v[74:77], v[34:49]
	ds_read_b128 v[74:77], v91 offset:32320
	s_waitcnt lgkmcnt(0)
	v_mfma_f32_32x32x16_bf16 v[34:49], v[74:77], v[70:73], v[34:49]
	ds_read_b128 v[70:73], v91 offset:32352
	s_waitcnt lgkmcnt(0)
	v_mfma_f32_32x32x16_bf16 v[34:49], v[70:73], v[66:69], v[34:49]
	v_max_f32_e32 v66, v51, v51
	v_max_f32_e32 v67, v50, v50
	v_max_f32_e32 v66, v67, v66
	v_max3_f32 v66, v66, v52, v53
	v_max3_f32 v66, v66, v54, v55
	v_max3_f32 v66, v66, v56, v57
	v_max3_f32 v66, v66, v58, v59
	v_max3_f32 v66, v66, v60, v61
	v_max3_f32 v66, v66, v62, v63
	v_max3_f32 v66, v66, v64, v65
	s_nop 1
	v_max3_f32 v66, v66, v34, v35
	v_max3_f32 v66, v66, v36, v37
	v_max3_f32 v66, v66, v38, v39
	v_max3_f32 v66, v66, v40, v41
	v_max3_f32 v66, v66, v42, v43
	v_max3_f32 v66, v66, v44, v45
	v_max3_f32 v66, v66, v46, v47
	v_max3_f32 v66, v66, v48, v49
	ds_bpermute_b32 v67, v177, v66
	s_waitcnt lgkmcnt(0)
	v_max3_f32 v66, v113, v66, v67
	v_sub_f32_e32 v50, v50, v66
	v_mul_f32_e32 v50, 0x3fb8aa3b, v50
	v_exp_f32_e32 v159, v50
	v_sub_f32_e32 v50, v51, v66
	v_mul_f32_e32 v50, 0x3fb8aa3b, v50
	v_exp_f32_e32 v161, v50
	v_sub_f32_e32 v50, v52, v66
	v_mul_f32_e32 v50, 0x3fb8aa3b, v50
	v_exp_f32_e32 v163, v50
	v_sub_f32_e32 v50, v53, v66
	v_mul_f32_e32 v50, 0x3fb8aa3b, v50
	v_exp_f32_e32 v165, v50
	v_sub_f32_e32 v50, v54, v66
	v_mul_f32_e32 v50, 0x3fb8aa3b, v50
	v_exp_f32_e32 v167, v50
	v_sub_f32_e32 v50, v55, v66
	v_mul_f32_e32 v50, 0x3fb8aa3b, v50
	v_exp_f32_e32 v169, v50
	v_sub_f32_e32 v50, v56, v66
	v_mul_f32_e32 v50, 0x3fb8aa3b, v50
	v_exp_f32_e32 v171, v50
	v_sub_f32_e32 v50, v57, v66
	v_mul_f32_e32 v50, 0x3fb8aa3b, v50
	v_sub_f32_e32 v52, v59, v66
	v_exp_f32_e32 v173, v50
	v_sub_f32_e32 v50, v58, v66
	v_mul_f32_e32 v52, 0x3fb8aa3b, v52
	v_mul_f32_e32 v50, 0x3fb8aa3b, v50
	v_exp_f32_e32 v127, v52
	v_sub_f32_e32 v52, v60, v66
	v_sub_f32_e32 v34, v34, v66
	v_exp_f32_e32 v125, v50
	v_pk_add_f32 v[50:51], v[158:159], v[174:175]
	v_mul_f32_e32 v52, 0x3fb8aa3b, v52
	v_mul_f32_e32 v34, 0x3fb8aa3b, v34
	v_pk_add_f32 v[50:51], v[160:161], v[50:51]
	v_exp_f32_e32 v131, v52
	v_sub_f32_e32 v52, v61, v66
	v_exp_f32_e32 v129, v34
	v_sub_f32_e32 v34, v35, v66
	v_pk_add_f32 v[50:51], v[162:163], v[50:51]
	v_mul_f32_e32 v52, 0x3fb8aa3b, v52
	v_mul_f32_e32 v34, 0x3fb8aa3b, v34
	v_pk_add_f32 v[50:51], v[164:165], v[50:51]
	v_exp_f32_e32 v135, v52
	v_sub_f32_e32 v52, v62, v66
	v_exp_f32_e32 v133, v34
	v_sub_f32_e32 v34, v36, v66
	v_sub_f32_e32 v36, v38, v66
	v_pk_add_f32 v[50:51], v[166:167], v[50:51]
	v_mul_f32_e32 v52, 0x3fb8aa3b, v52
	v_mul_f32_e32 v36, 0x3fb8aa3b, v36
	v_pk_add_f32 v[50:51], v[168:169], v[50:51]
	v_exp_f32_e32 v139, v52
	v_sub_f32_e32 v52, v63, v66
	v_exp_f32_e32 v145, v36
	v_sub_f32_e32 v36, v39, v66
	v_pk_add_f32 v[50:51], v[170:171], v[50:51]
	v_mul_f32_e32 v52, 0x3fb8aa3b, v52
	v_mul_f32_e32 v34, 0x3fb8aa3b, v34
	v_mul_f32_e32 v36, 0x3fb8aa3b, v36
	v_pk_add_f32 v[50:51], v[172:173], v[50:51]
	v_exp_f32_e32 v143, v52
	v_sub_f32_e32 v52, v64, v66
	v_exp_f32_e32 v137, v34
	v_sub_f32_e32 v34, v37, v66
	v_exp_f32_e32 v149, v36
	v_sub_f32_e32 v36, v40, v66
	v_pk_add_f32 v[50:51], v[124:125], v[50:51]
	v_mul_f32_e32 v52, 0x3fb8aa3b, v52
	v_mul_f32_e32 v34, 0x3fb8aa3b, v34
	v_mul_f32_e32 v36, 0x3fb8aa3b, v36
	v_exp_f32_e32 v147, v52
	v_sub_f32_e32 v52, v65, v66
	v_exp_f32_e32 v141, v34
	v_pk_add_f32 v[34:35], v[126:127], v[50:51]
	v_exp_f32_e32 v153, v36
	v_sub_f32_e32 v36, v41, v66
	v_mul_f32_e32 v52, 0x3fb8aa3b, v52
	v_pk_add_f32 v[34:35], v[130:131], v[34:35]
	v_mul_f32_e32 v36, 0x3fb8aa3b, v36
	v_exp_f32_e32 v151, v52
	v_pk_add_f32 v[34:35], v[134:135], v[34:35]
	v_exp_f32_e32 v155, v36
	v_sub_f32_e32 v36, v42, v66
	v_pk_add_f32 v[34:35], v[138:139], v[34:35]
	v_mul_f32_e32 v36, 0x3fb8aa3b, v36
	v_sub_f32_e32 v67, v113, v66
	v_pk_add_f32 v[34:35], v[142:143], v[34:35]
	v_exp_f32_e32 v113, v36
	v_sub_f32_e32 v36, v43, v66
	v_pk_add_f32 v[34:35], v[146:147], v[34:35]
	v_mul_f32_e32 v36, 0x3fb8aa3b, v36
	v_pk_add_f32 v[34:35], v[150:151], v[34:35]
	v_exp_f32_e32 v115, v36
	v_sub_f32_e32 v36, v44, v66
	v_pk_add_f32 v[34:35], v[128:129], v[34:35]
	v_mul_f32_e32 v36, 0x3fb8aa3b, v36
	v_pk_add_f32 v[34:35], v[132:133], v[34:35]
	v_exp_f32_e32 v117, v36
	v_sub_f32_e32 v36, v45, v66
	v_pk_add_f32 v[34:35], v[136:137], v[34:35]
	v_mul_f32_e32 v36, 0x3fb8aa3b, v36
	v_pk_add_f32 v[34:35], v[140:141], v[34:35]
	v_exp_f32_e32 v119, v36
	v_sub_f32_e32 v36, v46, v66
	v_mul_f32_e32 v36, 0x3fb8aa3b, v36
	v_pk_add_f32 v[34:35], v[144:145], v[34:35]
	v_exp_f32_e32 v121, v36
	v_sub_f32_e32 v36, v47, v66
	v_pk_add_f32 v[34:35], v[148:149], v[34:35]
	v_mul_f32_e32 v36, 0x3fb8aa3b, v36
	v_pk_add_f32 v[34:35], v[152:153], v[34:35]
	v_exp_f32_e32 v123, v36
	v_sub_f32_e32 v36, v48, v66
	v_pk_add_f32 v[34:35], v[154:155], v[34:35]
	v_mul_f32_e32 v67, 0x3fb8aa3b, v67
	v_mul_f32_e32 v36, 0x3fb8aa3b, v36
	v_pk_add_f32 v[34:35], v[112:113], v[34:35]
	v_exp_f32_e32 v157, v36
	v_sub_f32_e32 v36, v49, v66
	v_exp_f32_e32 v52, v67
; #define LAS __attribute__((address_space(3)))
; __device__ __forceinline__ unsigned pk2(float lo, float hi) { unsigned r; asm("v_cvt_pk_bf16_f32 %0, %1, %2" : "=v"(r) : "v"(lo), "v"(hi)); return r; }
; __device__ __forceinline__ void attn_chunk(LAS unsigned char* Kl, LAS unsigned char* Vl, const bf16x8 (&qf)[4], f32x16 (&o)[2], float& m, float& l, int q, int half, int ii, int maskmode) {
;     ...
;     for (int kb = 0; kb < 2; ++kb)
; #pragma unroll
;         for (int t = 0; t < 2; ++t) {
;             union { bf16x8 v; unsigned u[4]; } pf;
; #pragma unroll
;             for (int i = 0; i < 4; ++i) pf.u[i] = pk2(s[kb][8 * t + 2 * i], s[kb][8 * t + 2 * i + 1]);
; #pragma unroll
;             for (int db = 0; db < 2; ++db) {
;                 union { bf16x8 v; u32x2 h[2]; } vf;
;                 const LAS unsigned char* vp = Vl + (32 * db + q) * 136 + (32 * kb + 16 * t + 4 * half) * 2;
;                 vf.h[0] = *(const LAS u32x2*)vp; vf.h[1] = *(const LAS u32x2*)(vp + 16);
;                 o[db] = __builtin_amdgcn_mfma_f32_32x32x16_bf16(vf.v, pf.v, o[db], 0, 0, 0);
;             }
;         }
; __device__ __forceinline__ void attn_phase(const Params& P, LAS unsigned char* lds) {
;     ...
;         const float lt = l + __shfl_xor(l, 32), inv = 1.f / lt;
;         bf16_t* op = ao + (size_t)tok * D + h * 64;
; #pragma unroll
;         for (int db = 0; db < 2; ++db)
; #pragma unroll
;             for (int rg = 0; rg < 4; ++rg) { u32x2 ov; ov.x = pk2(o[db][4 * rg] * inv, o[db][4 * rg + 1] * inv); ov.y = pk2(o[db][4 * rg + 2] * inv, o[db][4 * rg + 3] * inv);
;                 *(u32x2*)(op + 32 * db + 8 * rg + 4 * half) = ov; }
;     }
	v_pk_add_f32 v[34:35], v[114:115], v[34:35]
	v_mul_f32_e32 v36, 0x3fb8aa3b, v36
	v_pk_add_f32 v[34:35], v[116:117], v[34:35]
	v_exp_f32_e32 v51, v36
	v_pk_add_f32 v[34:35], v[118:119], v[34:35]
	v_pk_mul_f32 v[44:45], v[12:13], v[52:53] op_sel_hi:[1,0]
	v_pk_add_f32 v[34:35], v[120:121], v[34:35]
	v_pk_mul_f32 v[42:43], v[10:11], v[52:53] op_sel_hi:[1,0]
	v_pk_add_f32 v[34:35], v[122:123], v[34:35]
	v_pk_mul_f32 v[40:41], v[8:9], v[52:53] op_sel_hi:[1,0]
	v_pk_mul_f32 v[38:39], v[6:7], v[52:53] op_sel_hi:[1,0]
	v_pk_mul_f32 v[12:13], v[28:29], v[52:53] op_sel_hi:[1,0]
	v_pk_mul_f32 v[10:11], v[26:27], v[52:53] op_sel_hi:[1,0]
	v_pk_mul_f32 v[8:9], v[24:25], v[52:53] op_sel_hi:[1,0]
	v_pk_mul_f32 v[6:7], v[22:23], v[52:53] op_sel_hi:[1,0]
	ds_read2_b64 v[22:25], v216 offset0:192 offset1:194
	ds_read2_b64 v[26:29], v216 offset0:196 offset1:198
	v_pk_add_f32 v[34:35], v[156:157], v[34:35]
	v_pk_mul_f32 v[48:49], v[16:17], v[52:53] op_sel_hi:[1,0]
	v_add_f32_e32 v50, v35, v51
	v_fmac_f32_e32 v50, v34, v52
	v_pk_mul_f32 v[46:47], v[14:15], v[52:53] op_sel_hi:[1,0]
	v_pk_mul_f32 v[36:37], v[4:5], v[52:53] op_sel_hi:[1,0]
	v_pk_mul_f32 v[34:35], v[2:3], v[52:53] op_sel_hi:[1,0]
	v_pk_mul_f32 v[4:5], v[20:21], v[52:53] op_sel_hi:[1,0]
	v_pk_mul_f32 v[2:3], v[18:19], v[52:53] op_sel_hi:[1,0]
	v_cvt_pk_bf16_f32 v18, v159, v161
	v_cvt_pk_bf16_f32 v19, v163, v165
	v_cvt_pk_bf16_f32 v20, v167, v169
	v_cvt_pk_bf16_f32 v21, v171, v173
	v_pk_mul_f32 v[16:17], v[32:33], v[52:53] op_sel_hi:[1,0]
	s_waitcnt lgkmcnt(1)
	v_mfma_f32_32x32x16_bf16 v[34:49], v[22:25], v[18:21], v[34:49]
	ds_read2_b64 v[22:25], v195 offset0:224 offset1:226
	v_mul_f32_e64 v14, v30, v52
	v_mul_f32_e64 v15, v31, v52
	s_waitcnt lgkmcnt(0)
	s_nop 0
	v_mfma_f32_32x32x16_bf16 v[2:17], v[22:25], v[18:21], v[2:17]
	ds_read2_b64 v[22:25], v195 offset0:228 offset1:230
	v_cvt_pk_bf16_f32 v18, v125, v127
	v_cvt_pk_bf16_f32 v19, v131, v135
	v_cvt_pk_bf16_f32 v20, v139, v143
	v_cvt_pk_bf16_f32 v21, v147, v151
	s_waitcnt lgkmcnt(0)
	v_mfma_f32_32x32x16_bf16 v[2:17], v[22:25], v[18:21], v[2:17]
	ds_read2_b64 v[22:25], v216 offset0:200 offset1:202
	v_mfma_f32_32x32x16_bf16 v[34:49], v[26:29], v[18:21], v[34:49]
	v_cvt_pk_bf16_f32 v18, v129, v133
	v_cvt_pk_bf16_f32 v19, v137, v141
	v_cvt_pk_bf16_f32 v20, v145, v149
	v_cvt_pk_bf16_f32 v21, v153, v155
	s_waitcnt lgkmcnt(0)
	v_mfma_f32_32x32x16_bf16 v[34:49], v[22:25], v[18:21], v[34:49]
	ds_read2_b64 v[22:25], v195 offset0:232 offset1:234
	s_waitcnt lgkmcnt(0)
	v_mfma_f32_32x32x16_bf16 v[2:17], v[22:25], v[18:21], v[2:17]
	ds_read2_b64 v[22:25], v216 offset0:204 offset1:206
	v_cvt_pk_bf16_f32 v18, v113, v115
	v_cvt_pk_bf16_f32 v19, v117, v119
	v_cvt_pk_bf16_f32 v20, v121, v123
	v_cvt_pk_bf16_f32 v21, v157, v51
	s_waitcnt lgkmcnt(0)
	v_mfma_f32_32x32x16_bf16 v[34:49], v[22:25], v[18:21], v[34:49]
	ds_read2_b64 v[22:25], v195 offset0:236 offset1:238
	s_waitcnt lgkmcnt(0)
	s_barrier
	v_mfma_f32_32x32x16_bf16 v[2:17], v[22:25], v[18:21], v[2:17]
	ds_bpermute_b32 v18, v177, v50
	s_waitcnt lgkmcnt(0)
	v_add_f32_e32 v18, v50, v18
	v_div_scale_f32 v19, s[0:1], v18, v18, 1.0
	v_rcp_f32_e32 v20, v19
	v_readlane_b32 s0, v250, 27
	v_readlane_b32 s1, v250, 28
	v_fma_f32 v21, -v19, v20, 1.0
	v_fmac_f32_e32 v20, v21, v20
	v_div_scale_f32 v21, vcc, 1.0, v18, 1.0
	v_mul_f32_e32 v22, v21, v20
	v_fma_f32 v23, -v19, v22, v21
	v_fmac_f32_e32 v22, v23, v20
	v_fma_f32 v19, -v19, v22, v21
	v_div_fmas_f32 v19, v19, v20, v22
	v_div_fixup_f32 v22, v19, v18, 1.0
	v_lshlrev_b64 v[18:19], 11, v[108:109]
	v_lshl_add_u64 v[18:19], s[0:1], 0, v[18:19]
	v_mul_f32_e32 v20, v34, v22
	v_mul_f32_e32 v21, v35, v22
	v_mul_f32_e32 v2, v2, v22
	v_mul_f32_e32 v3, v3, v22
	v_lshl_add_u64 v[18:19], v[110:111], 1, v[18:19]
	v_cvt_pk_bf16_f32 v20, v20, v21
	v_mul_f32_e32 v21, v36, v22
	v_cvt_pk_bf16_f32 v2, v2, v3
	v_mul_f32_e32 v3, v4, v22
	v_lshl_add_u64 v[18:19], v[18:19], 0, v[106:107]
	v_mul_f32_e32 v23, v37, v22
	v_cvt_pk_bf16_f32 v21, v21, v23
	v_mul_f32_e32 v4, v5, v22
	v_cvt_pk_bf16_f32 v3, v3, v4
	global_store_dwordx2 v[18:19], v[20:21], off
	v_mul_f32_e32 v20, v38, v22
	v_mul_f32_e32 v21, v39, v22
	global_store_dwordx2 v[18:19], v[2:3], off offset:64
	v_mul_f32_e32 v2, v6, v22
	v_mul_f32_e32 v3, v7, v22
	v_cvt_pk_bf16_f32 v20, v20, v21
	v_mul_f32_e32 v21, v40, v22
	v_cvt_pk_bf16_f32 v2, v2, v3
	v_mul_f32_e32 v3, v8, v22
	v_mul_f32_e32 v23, v41, v22
	v_cvt_pk_bf16_f32 v21, v21, v23
	v_mul_f32_e32 v4, v9, v22
	v_cvt_pk_bf16_f32 v3, v3, v4
	global_store_dwordx2 v[18:19], v[20:21], off offset:16
	v_mul_f32_e32 v20, v42, v22
	v_mul_f32_e32 v21, v43, v22
	global_store_dwordx2 v[18:19], v[2:3], off offset:80
	v_mul_f32_e32 v2, v10, v22
	v_mul_f32_e32 v3, v11, v22
	v_cvt_pk_bf16_f32 v20, v20, v21
	v_mul_f32_e32 v21, v44, v22
	v_cvt_pk_bf16_f32 v2, v2, v3
	v_mul_f32_e32 v3, v12, v22
	v_mul_f32_e32 v23, v45, v22
	v_cvt_pk_bf16_f32 v21, v21, v23
	v_mul_f32_e32 v4, v13, v22
	v_cvt_pk_bf16_f32 v3, v3, v4
	global_store_dwordx2 v[18:19], v[20:21], off offset:32
	v_mul_f32_e32 v20, v46, v22
	v_mul_f32_e32 v21, v47, v22
	global_store_dwordx2 v[18:19], v[2:3], off offset:96
	v_mul_f32_e32 v2, v14, v22
	v_mul_f32_e32 v3, v15, v22
	v_cvt_pk_bf16_f32 v20, v20, v21
	v_mul_f32_e32 v21, v48, v22
	v_cvt_pk_bf16_f32 v2, v2, v3
	v_mul_f32_e32 v3, v16, v22
	v_mul_f32_e32 v23, v49, v22
	v_cvt_pk_bf16_f32 v21, v21, v23
	global_store_dwordx2 v[18:19], v[20:21], off offset:48
	v_mul_f32_e32 v4, v17, v22
	v_cvt_pk_bf16_f32 v3, v3, v4
	global_store_dwordx2 v[18:19], v[2:3], off offset:112
	s_load_dword s0, s[50:51], 0x0
	s_waitcnt lgkmcnt(0)
	s_add_i32 s34, s0, s34
	s_cmpk_gt_i32 s34, 0x3ff
	s_cbranch_scc1 .LBB0_744
